# P4 compress stage 2 epilogue: rope pair requested at the top of the row epilogue (overlaps wave sum and sqrt/div)
# baseline (speedup 1.0000x reference)
.LBB0_654:
	s_andn2_b64 vcc, exec, s[2:3]
	s_cbranch_vccnz .LBB0_647
	v_mov_b32_e32 v6, v215
	s_lshl_b32 s88, s27, 4
	s_ashr_i32 s89, s88, 31
	s_lshl_b64 s[88:89], s[88:89], 8
	v_lshl_add_u64 v[216:217], v[14:15], 0, s[88:89]
	v_lshl_add_u64 v[216:217], v[216:217], 0, s[8:9]
	global_load_dwordx2 v[218:219], v[216:217], off
	v_mul_f32_e32 v9, v11, v11
	v_xor_b32_e32 v17, 32, v22
	v_cmp_lt_i32_e32 vcc, v17, v26
	v_add_f32_dpp v9, v9, v9 quad_perm:[1,0,3,2] row_mask:0xf bank_mask:0xf
	s_nop 1
	v_add_f32_dpp v9, v9, v9 quad_perm:[2,3,0,1] row_mask:0xf bank_mask:0xf
	v_cndmask_b32_e32 v17, v22, v17, vcc
	s_nop 0
	v_add_f32_dpp v9, v9, v9 row_half_mirror row_mask:0xf bank_mask:0xf
	v_lshlrev_b32_e32 v17, 2, v17
	s_nop 0
	v_add_f32_dpp v9, v9, v9 row_mirror row_mask:0xf bank_mask:0xf
	s_nop 0
	v_mov_b32_e32 v16, v9
	s_nop 1
	v_permlane16_swap_b32 v9, v16
	s_nop 0
	v_add_f32_e32 v9, v9, v16
	v_mov_b32_e32 v16, v9
	s_nop 1
	v_permlane32_swap_b32 v9, v16
	s_nop 0
	v_add_f32_e32 v9, v9, v16
	v_fmamk_f32 v9, v9, 0x3c800000, v20
	v_mul_f32_e32 v16, 0x4f800000, v9
	v_cmp_gt_f32_e32 vcc, s20, v9
	s_nop 1
	v_cndmask_b32_e32 v9, v9, v16, vcc
	v_sqrt_f32_e32 v16, v9
	s_nop 0
	v_add_u32_e32 v18, -1, v16
	v_add_u32_e32 v19, 1, v16
	v_fma_f32 v27, -v18, v16, v9
	v_fma_f32 v28, -v19, v16, v9
	v_cmp_ge_f32_e64 s[2:3], 0, v27
	s_nop 1
	v_cndmask_b32_e64 v16, v16, v18, s[2:3]
	v_cmp_lt_f32_e64 s[2:3], 0, v28
	s_nop 1
	v_cndmask_b32_e64 v16, v16, v19, s[2:3]
	v_mul_f32_e32 v18, 0x37800000, v16
	v_cndmask_b32_e32 v16, v16, v18, vcc
	v_cmp_class_f32_e32 vcc, v9, v21
	s_nop 1
	v_cndmask_b32_e32 v9, v16, v9, vcc
	v_div_scale_f32 v16, s[2:3], v9, v9, 1.0
	v_rcp_f32_e32 v18, v16
	v_div_scale_f32 v19, vcc, 1.0, v9, 1.0
	s_lshl_b32 s2, s27, 4
	v_fma_f32 v27, -v16, v18, 1.0
	v_fmac_f32_e32 v18, v27, v18
	v_mul_f32_e32 v27, v19, v18
	v_fma_f32 v28, -v16, v27, v19
	v_fmac_f32_e32 v27, v28, v18
	v_fma_f32 v16, -v16, v27, v19
	v_div_fmas_f32 v16, v16, v18, v27
	v_div_fixup_f32 v9, v16, v9, 1.0
	v_mul_f32_e32 v9, v11, v9
	s_nop 0
	v_mul_f32_e32 v16, v6, v9
	ds_bpermute_b32 v17, v17, v16
	s_ashr_i32 s3, s2, 31
	s_lshl_b64 s[2:3], s[2:3], 8
	v_lshl_add_u64 v[18:19], v[14:15], 0, s[2:3]
	v_lshl_add_u64 v[18:19], v[18:19], 0, s[8:9]
	s_and_saveexec_b64 s[2:3], s[0:1]
	s_xor_b64 s[2:3], exec, s[2:3]
	s_cbranch_execz .LBB0_657
	s_nop 0
	s_waitcnt vmcnt(0) lgkmcnt(0)
	v_pk_mul_f32 v[16:17], v[218:219], v[16:17]
	s_nop 0
	v_add_f32_e32 v6, v17, v16
.LBB0_657:
	s_andn2_saveexec_b64 s[2:3], s[2:3]
	s_cbranch_execz .LBB0_659
	s_nop 0
	s_waitcnt vmcnt(0) lgkmcnt(0)
	v_pk_mul_f32 v[16:17], v[16:17], v[218:219]
	s_nop 0
	v_sub_f32_e32 v6, v16, v17
